# non-temporal hint also on the gate loads of the mix-phase GEMM-unit epilogues
# baseline (speedup 1.0000x reference)
.LBB0_1086:
	s_waitcnt vmcnt(0)
	s_mov_b64 s[4:5], -1
	s_and_b64 vcc, exec, s[20:21]
	s_barrier
	s_cbranch_vccz .LBB0_1152
	v_ashrrev_i32_e32 v3, 1, v144
	s_movk_i32 s4, 0xff80
	v_and_or_b32 v3, v3, s4, v161
	v_and_b32_e32 v5, 0xc0, v144
	v_and_b32_e32 v2, 4, v145
	v_add_u32_e32 v5, v5, v2
	v_lshlrev_b32_e32 v2, 2, v5
	v_lshlrev_b32_e32 v5, 1, v5
	v_mad_u32_u24 v0, v3, s92, v5
	v_lshl_add_u32 v1, v3, 11, v5
	v_readlane_b32 s70, v254, 8
	v_readlane_b32 s71, v254, 9
	s_mul_i32 s4, s68, 0xa00
	s_lshl_b32 s5, s14, 1
	s_add_u32 s4, s4, s5
	s_add_u32 s70, s70, s4
	s_addc_u32 s71, s71, 0
	s_lshl_b32 s4, s68, 11
	s_lshl_b32 s5, s12, 1
	s_add_u32 s4, s4, s5
	s_add_u32 s72, s46, s4
	s_addc_u32 s73, s47, 0
	s_cmp_lg_u64 s[0:1], 0
	s_cbranch_scc1 .Lgepi_scale
	s_add_u32 s74, s70, 0x0
	s_addc_u32 s75, s71, 0
	global_load_dwordx2 v[146:147], v0, s[74:75] nt
	global_load_dwordx2 v[148:149], v0, s[74:75] offset:16 nt
	global_load_dwordx2 v[150:151], v0, s[74:75] offset:32 nt
	global_load_dwordx2 v[152:153], v0, s[74:75] offset:48 nt
	global_load_dwordx2 v[154:155], v0, s[74:75] offset:64 nt
	global_load_dwordx2 v[156:157], v0, s[74:75] offset:80 nt
	global_load_dwordx2 v[158:159], v0, s[74:75] offset:96 nt
	global_load_dwordx2 v[160:161], v0, s[74:75] offset:112 nt
	s_add_u32 s74, s70, 0x14000
	s_addc_u32 s75, s71, 0
	global_load_dwordx2 v[162:163], v0, s[74:75] nt
	global_load_dwordx2 v[164:165], v0, s[74:75] offset:16 nt
	global_load_dwordx2 v[166:167], v0, s[74:75] offset:32 nt
	global_load_dwordx2 v[168:169], v0, s[74:75] offset:48 nt
	global_load_dwordx2 v[170:171], v0, s[74:75] offset:64 nt
	global_load_dwordx2 v[172:173], v0, s[74:75] offset:80 nt
	global_load_dwordx2 v[174:175], v0, s[74:75] offset:96 nt
	global_load_dwordx2 v[176:177], v0, s[74:75] offset:112 nt
	s_add_u32 s74, s70, 0x28000
	s_addc_u32 s75, s71, 0
	global_load_dwordx2 v[178:179], v0, s[74:75] nt
	global_load_dwordx2 v[180:181], v0, s[74:75] offset:16 nt
	global_load_dwordx2 v[182:183], v0, s[74:75] offset:32 nt
	global_load_dwordx2 v[184:185], v0, s[74:75] offset:48 nt
	global_load_dwordx2 v[186:187], v0, s[74:75] offset:64 nt
	global_load_dwordx2 v[188:189], v0, s[74:75] offset:80 nt
	global_load_dwordx2 v[190:191], v0, s[74:75] offset:96 nt
	global_load_dwordx2 v[192:193], v0, s[74:75] offset:112 nt
	s_add_u32 s74, s70, 0x3c000
	s_addc_u32 s75, s71, 0
	global_load_dwordx2 v[194:195], v0, s[74:75] nt
	global_load_dwordx2 v[196:197], v0, s[74:75] offset:16 nt
	global_load_dwordx2 v[198:199], v0, s[74:75] offset:32 nt
	global_load_dwordx2 v[200:201], v0, s[74:75] offset:48 nt
	global_load_dwordx2 v[202:203], v0, s[74:75] offset:64 nt
	global_load_dwordx2 v[204:205], v0, s[74:75] offset:80 nt
	global_load_dwordx2 v[206:207], v0, s[74:75] offset:96 nt
	global_load_dwordx2 v[208:209], v0, s[74:75] offset:112 nt
	s_add_u32 s74, s72, 0x0
	s_addc_u32 s75, s73, 0
	s_waitcnt vmcnt(31)
	v_and_b32_e32 v3, 0xffff0000, v146
	v_lshlrev_b32_e32 v2, 16, v146
	v_pk_mul_f32 v[118:119], v[118:119], v[2:3]
	v_and_b32_e32 v3, 0xffff0000, v147
	v_lshlrev_b32_e32 v2, 16, v147
	v_pk_mul_f32 v[120:121], v[120:121], v[2:3]
	v_cvt_pk_bf16_f32 v146, v118, v119
	v_cvt_pk_bf16_f32 v147, v120, v121
	global_store_dwordx2 v1, v[146:147], s[74:75]
	s_waitcnt vmcnt(31)
	v_and_b32_e32 v3, 0xffff0000, v148
	v_lshlrev_b32_e32 v2, 16, v148
	v_pk_mul_f32 v[122:123], v[122:123], v[2:3]
	v_and_b32_e32 v3, 0xffff0000, v149
	v_lshlrev_b32_e32 v2, 16, v149
	v_pk_mul_f32 v[124:125], v[124:125], v[2:3]
	v_cvt_pk_bf16_f32 v148, v122, v123
	v_cvt_pk_bf16_f32 v149, v124, v125
	global_store_dwordx2 v1, v[148:149], s[74:75] offset:16
	s_waitcnt vmcnt(31)
	v_and_b32_e32 v3, 0xffff0000, v150
	v_lshlrev_b32_e32 v2, 16, v150
	v_pk_mul_f32 v[126:127], v[126:127], v[2:3]
	v_and_b32_e32 v3, 0xffff0000, v151
	v_lshlrev_b32_e32 v2, 16, v151
	v_pk_mul_f32 v[128:129], v[128:129], v[2:3]
	v_cvt_pk_bf16_f32 v150, v126, v127
	v_cvt_pk_bf16_f32 v151, v128, v129
	global_store_dwordx2 v1, v[150:151], s[74:75] offset:32
	s_waitcnt vmcnt(31)
	v_and_b32_e32 v3, 0xffff0000, v152
	v_lshlrev_b32_e32 v2, 16, v152
	v_pk_mul_f32 v[130:131], v[130:131], v[2:3]
	v_and_b32_e32 v3, 0xffff0000, v153
	v_lshlrev_b32_e32 v2, 16, v153
	v_pk_mul_f32 v[132:133], v[132:133], v[2:3]
	v_cvt_pk_bf16_f32 v152, v130, v131
	v_cvt_pk_bf16_f32 v153, v132, v133
	global_store_dwordx2 v1, v[152:153], s[74:75] offset:48
	s_waitcnt vmcnt(31)
	v_and_b32_e32 v3, 0xffff0000, v154
	v_lshlrev_b32_e32 v2, 16, v154
	v_pk_mul_f32 v[102:103], v[102:103], v[2:3]
	v_and_b32_e32 v3, 0xffff0000, v155
	v_lshlrev_b32_e32 v2, 16, v155
	v_pk_mul_f32 v[104:105], v[104:105], v[2:3]
	v_cvt_pk_bf16_f32 v154, v102, v103
	v_cvt_pk_bf16_f32 v155, v104, v105
	global_store_dwordx2 v1, v[154:155], s[74:75] offset:64
	s_waitcnt vmcnt(31)
	v_and_b32_e32 v3, 0xffff0000, v156
	v_lshlrev_b32_e32 v2, 16, v156
	v_pk_mul_f32 v[106:107], v[106:107], v[2:3]
	v_and_b32_e32 v3, 0xffff0000, v157
	v_lshlrev_b32_e32 v2, 16, v157
	v_pk_mul_f32 v[108:109], v[108:109], v[2:3]
	v_cvt_pk_bf16_f32 v156, v106, v107
	v_cvt_pk_bf16_f32 v157, v108, v109
	global_store_dwordx2 v1, v[156:157], s[74:75] offset:80
	s_waitcnt vmcnt(31)
	v_and_b32_e32 v3, 0xffff0000, v158
	v_lshlrev_b32_e32 v2, 16, v158
	v_pk_mul_f32 v[110:111], v[110:111], v[2:3]
	v_and_b32_e32 v3, 0xffff0000, v159
	v_lshlrev_b32_e32 v2, 16, v159
	v_pk_mul_f32 v[112:113], v[112:113], v[2:3]
	v_cvt_pk_bf16_f32 v158, v110, v111
	v_cvt_pk_bf16_f32 v159, v112, v113
	global_store_dwordx2 v1, v[158:159], s[74:75] offset:96
	s_waitcnt vmcnt(31)
	v_and_b32_e32 v3, 0xffff0000, v160
	v_lshlrev_b32_e32 v2, 16, v160
	v_pk_mul_f32 v[114:115], v[114:115], v[2:3]
	v_and_b32_e32 v3, 0xffff0000, v161
	v_lshlrev_b32_e32 v2, 16, v161
	v_pk_mul_f32 v[116:117], v[116:117], v[2:3]
	v_cvt_pk_bf16_f32 v160, v114, v115
	v_cvt_pk_bf16_f32 v161, v116, v117
	global_store_dwordx2 v1, v[160:161], s[74:75] offset:112
	s_add_u32 s74, s72, 0x10000
	s_addc_u32 s75, s73, 0
	s_waitcnt vmcnt(31)
	v_and_b32_e32 v3, 0xffff0000, v162
	v_lshlrev_b32_e32 v2, 16, v162
	v_pk_mul_f32 v[86:87], v[86:87], v[2:3]
	v_and_b32_e32 v3, 0xffff0000, v163
	v_lshlrev_b32_e32 v2, 16, v163
	v_pk_mul_f32 v[88:89], v[88:89], v[2:3]
	v_cvt_pk_bf16_f32 v162, v86, v87
	v_cvt_pk_bf16_f32 v163, v88, v89
	global_store_dwordx2 v1, v[162:163], s[74:75]
	s_waitcnt vmcnt(31)
	v_and_b32_e32 v3, 0xffff0000, v164
	v_lshlrev_b32_e32 v2, 16, v164
	v_pk_mul_f32 v[90:91], v[90:91], v[2:3]
	v_and_b32_e32 v3, 0xffff0000, v165
	v_lshlrev_b32_e32 v2, 16, v165
	v_pk_mul_f32 v[92:93], v[92:93], v[2:3]
	v_cvt_pk_bf16_f32 v164, v90, v91
	v_cvt_pk_bf16_f32 v165, v92, v93
	global_store_dwordx2 v1, v[164:165], s[74:75] offset:16
	s_waitcnt vmcnt(31)
	v_and_b32_e32 v3, 0xffff0000, v166
	v_lshlrev_b32_e32 v2, 16, v166
	v_pk_mul_f32 v[94:95], v[94:95], v[2:3]
	v_and_b32_e32 v3, 0xffff0000, v167
	v_lshlrev_b32_e32 v2, 16, v167
	v_pk_mul_f32 v[96:97], v[96:97], v[2:3]
	v_cvt_pk_bf16_f32 v166, v94, v95
	v_cvt_pk_bf16_f32 v167, v96, v97
	global_store_dwordx2 v1, v[166:167], s[74:75] offset:32
	s_waitcnt vmcnt(31)
	v_and_b32_e32 v3, 0xffff0000, v168
	v_lshlrev_b32_e32 v2, 16, v168
	v_pk_mul_f32 v[98:99], v[98:99], v[2:3]
	v_and_b32_e32 v3, 0xffff0000, v169
	v_lshlrev_b32_e32 v2, 16, v169
	v_pk_mul_f32 v[100:101], v[100:101], v[2:3]
	v_cvt_pk_bf16_f32 v168, v98, v99
	v_cvt_pk_bf16_f32 v169, v100, v101
	global_store_dwordx2 v1, v[168:169], s[74:75] offset:48
	s_waitcnt vmcnt(31)
	v_and_b32_e32 v3, 0xffff0000, v170
	v_lshlrev_b32_e32 v2, 16, v170
	v_pk_mul_f32 v[70:71], v[70:71], v[2:3]
	v_and_b32_e32 v3, 0xffff0000, v171
	v_lshlrev_b32_e32 v2, 16, v171
	v_pk_mul_f32 v[72:73], v[72:73], v[2:3]
	v_cvt_pk_bf16_f32 v170, v70, v71
	v_cvt_pk_bf16_f32 v171, v72, v73
	global_store_dwordx2 v1, v[170:171], s[74:75] offset:64
	s_waitcnt vmcnt(31)
	v_and_b32_e32 v3, 0xffff0000, v172
	v_lshlrev_b32_e32 v2, 16, v172
	v_pk_mul_f32 v[74:75], v[74:75], v[2:3]
	v_and_b32_e32 v3, 0xffff0000, v173
	v_lshlrev_b32_e32 v2, 16, v173
	v_pk_mul_f32 v[76:77], v[76:77], v[2:3]
	v_cvt_pk_bf16_f32 v172, v74, v75
	v_cvt_pk_bf16_f32 v173, v76, v77
	global_store_dwordx2 v1, v[172:173], s[74:75] offset:80
	s_waitcnt vmcnt(31)
	v_and_b32_e32 v3, 0xffff0000, v174
	v_lshlrev_b32_e32 v2, 16, v174
	v_pk_mul_f32 v[78:79], v[78:79], v[2:3]
	v_and_b32_e32 v3, 0xffff0000, v175
	v_lshlrev_b32_e32 v2, 16, v175
	v_pk_mul_f32 v[80:81], v[80:81], v[2:3]
	v_cvt_pk_bf16_f32 v174, v78, v79
	v_cvt_pk_bf16_f32 v175, v80, v81
	global_store_dwordx2 v1, v[174:175], s[74:75] offset:96
	s_waitcnt vmcnt(31)
	v_and_b32_e32 v3, 0xffff0000, v176
	v_lshlrev_b32_e32 v2, 16, v176
	v_pk_mul_f32 v[82:83], v[82:83], v[2:3]
	v_and_b32_e32 v3, 0xffff0000, v177
	v_lshlrev_b32_e32 v2, 16, v177
	v_pk_mul_f32 v[84:85], v[84:85], v[2:3]
	v_cvt_pk_bf16_f32 v176, v82, v83
	v_cvt_pk_bf16_f32 v177, v84, v85
	global_store_dwordx2 v1, v[176:177], s[74:75] offset:112
	s_add_u32 s74, s72, 0x20000
	s_addc_u32 s75, s73, 0
	s_waitcnt vmcnt(31)
	v_and_b32_e32 v3, 0xffff0000, v178
	v_lshlrev_b32_e32 v2, 16, v178
	v_pk_mul_f32 v[54:55], v[54:55], v[2:3]
	v_and_b32_e32 v3, 0xffff0000, v179
	v_lshlrev_b32_e32 v2, 16, v179
	v_pk_mul_f32 v[56:57], v[56:57], v[2:3]
	v_cvt_pk_bf16_f32 v178, v54, v55
	v_cvt_pk_bf16_f32 v179, v56, v57
	global_store_dwordx2 v1, v[178:179], s[74:75]
	s_waitcnt vmcnt(31)
	v_and_b32_e32 v3, 0xffff0000, v180
	v_lshlrev_b32_e32 v2, 16, v180
	v_pk_mul_f32 v[58:59], v[58:59], v[2:3]
	v_and_b32_e32 v3, 0xffff0000, v181
	v_lshlrev_b32_e32 v2, 16, v181
	v_pk_mul_f32 v[60:61], v[60:61], v[2:3]
	v_cvt_pk_bf16_f32 v180, v58, v59
	v_cvt_pk_bf16_f32 v181, v60, v61
	global_store_dwordx2 v1, v[180:181], s[74:75] offset:16
	s_waitcnt vmcnt(31)
	v_and_b32_e32 v3, 0xffff0000, v182
	v_lshlrev_b32_e32 v2, 16, v182
	v_pk_mul_f32 v[62:63], v[62:63], v[2:3]
	v_and_b32_e32 v3, 0xffff0000, v183
	v_lshlrev_b32_e32 v2, 16, v183
	v_pk_mul_f32 v[64:65], v[64:65], v[2:3]
	v_cvt_pk_bf16_f32 v182, v62, v63
	v_cvt_pk_bf16_f32 v183, v64, v65
	global_store_dwordx2 v1, v[182:183], s[74:75] offset:32
	s_waitcnt vmcnt(31)
	v_and_b32_e32 v3, 0xffff0000, v184
	v_lshlrev_b32_e32 v2, 16, v184
	v_pk_mul_f32 v[66:67], v[66:67], v[2:3]
	v_and_b32_e32 v3, 0xffff0000, v185
	v_lshlrev_b32_e32 v2, 16, v185
	v_pk_mul_f32 v[68:69], v[68:69], v[2:3]
	v_cvt_pk_bf16_f32 v184, v66, v67
	v_cvt_pk_bf16_f32 v185, v68, v69
	global_store_dwordx2 v1, v[184:185], s[74:75] offset:48
	s_waitcnt vmcnt(31)
	v_and_b32_e32 v3, 0xffff0000, v186
	v_lshlrev_b32_e32 v2, 16, v186
	v_pk_mul_f32 v[38:39], v[38:39], v[2:3]
	v_and_b32_e32 v3, 0xffff0000, v187
	v_lshlrev_b32_e32 v2, 16, v187
	v_pk_mul_f32 v[40:41], v[40:41], v[2:3]
	v_cvt_pk_bf16_f32 v186, v38, v39
	v_cvt_pk_bf16_f32 v187, v40, v41
	global_store_dwordx2 v1, v[186:187], s[74:75] offset:64
	s_waitcnt vmcnt(31)
	v_and_b32_e32 v3, 0xffff0000, v188
	v_lshlrev_b32_e32 v2, 16, v188
	v_pk_mul_f32 v[42:43], v[42:43], v[2:3]
	v_and_b32_e32 v3, 0xffff0000, v189
	v_lshlrev_b32_e32 v2, 16, v189
	v_pk_mul_f32 v[44:45], v[44:45], v[2:3]
	v_cvt_pk_bf16_f32 v188, v42, v43
	v_cvt_pk_bf16_f32 v189, v44, v45
	global_store_dwordx2 v1, v[188:189], s[74:75] offset:80
	s_waitcnt vmcnt(31)
	v_and_b32_e32 v3, 0xffff0000, v190
	v_lshlrev_b32_e32 v2, 16, v190
	v_pk_mul_f32 v[46:47], v[46:47], v[2:3]
	v_and_b32_e32 v3, 0xffff0000, v191
	v_lshlrev_b32_e32 v2, 16, v191
	v_pk_mul_f32 v[48:49], v[48:49], v[2:3]
	v_cvt_pk_bf16_f32 v190, v46, v47
	v_cvt_pk_bf16_f32 v191, v48, v49
	global_store_dwordx2 v1, v[190:191], s[74:75] offset:96
	s_waitcnt vmcnt(31)
	v_and_b32_e32 v3, 0xffff0000, v192
	v_lshlrev_b32_e32 v2, 16, v192
	v_pk_mul_f32 v[50:51], v[50:51], v[2:3]
	v_and_b32_e32 v3, 0xffff0000, v193
	v_lshlrev_b32_e32 v2, 16, v193
	v_pk_mul_f32 v[52:53], v[52:53], v[2:3]
	v_cvt_pk_bf16_f32 v192, v50, v51
	v_cvt_pk_bf16_f32 v193, v52, v53
	global_store_dwordx2 v1, v[192:193], s[74:75] offset:112
	s_add_u32 s74, s72, 0x30000
	s_addc_u32 s75, s73, 0
	s_waitcnt vmcnt(31)
	v_and_b32_e32 v3, 0xffff0000, v194
	v_lshlrev_b32_e32 v2, 16, v194
	v_pk_mul_f32 v[22:23], v[22:23], v[2:3]
	v_and_b32_e32 v3, 0xffff0000, v195
	v_lshlrev_b32_e32 v2, 16, v195
	v_pk_mul_f32 v[24:25], v[24:25], v[2:3]
	v_cvt_pk_bf16_f32 v194, v22, v23
	v_cvt_pk_bf16_f32 v195, v24, v25
	global_store_dwordx2 v1, v[194:195], s[74:75]
	s_waitcnt vmcnt(31)
	v_and_b32_e32 v3, 0xffff0000, v196
	v_lshlrev_b32_e32 v2, 16, v196
	v_pk_mul_f32 v[26:27], v[26:27], v[2:3]
	v_and_b32_e32 v3, 0xffff0000, v197
	v_lshlrev_b32_e32 v2, 16, v197
	v_pk_mul_f32 v[28:29], v[28:29], v[2:3]
	v_cvt_pk_bf16_f32 v196, v26, v27
	v_cvt_pk_bf16_f32 v197, v28, v29
	global_store_dwordx2 v1, v[196:197], s[74:75] offset:16
	s_waitcnt vmcnt(31)
	v_and_b32_e32 v3, 0xffff0000, v198
	v_lshlrev_b32_e32 v2, 16, v198
	v_pk_mul_f32 v[30:31], v[30:31], v[2:3]
	v_and_b32_e32 v3, 0xffff0000, v199
	v_lshlrev_b32_e32 v2, 16, v199
	v_pk_mul_f32 v[32:33], v[32:33], v[2:3]
	v_cvt_pk_bf16_f32 v198, v30, v31
	v_cvt_pk_bf16_f32 v199, v32, v33
	global_store_dwordx2 v1, v[198:199], s[74:75] offset:32
	s_waitcnt vmcnt(31)
	v_and_b32_e32 v3, 0xffff0000, v200
	v_lshlrev_b32_e32 v2, 16, v200
	v_pk_mul_f32 v[34:35], v[34:35], v[2:3]
	v_and_b32_e32 v3, 0xffff0000, v201
	v_lshlrev_b32_e32 v2, 16, v201
	v_pk_mul_f32 v[36:37], v[36:37], v[2:3]
	v_cvt_pk_bf16_f32 v200, v34, v35
	v_cvt_pk_bf16_f32 v201, v36, v37
	global_store_dwordx2 v1, v[200:201], s[74:75] offset:48
	s_waitcnt vmcnt(31)
	v_and_b32_e32 v3, 0xffff0000, v202
	v_lshlrev_b32_e32 v2, 16, v202
	v_pk_mul_f32 v[6:7], v[6:7], v[2:3]
	v_and_b32_e32 v3, 0xffff0000, v203
	v_lshlrev_b32_e32 v2, 16, v203
	v_pk_mul_f32 v[8:9], v[8:9], v[2:3]
	v_cvt_pk_bf16_f32 v202, v6, v7
	v_cvt_pk_bf16_f32 v203, v8, v9
	global_store_dwordx2 v1, v[202:203], s[74:75] offset:64
	s_waitcnt vmcnt(31)
	v_and_b32_e32 v3, 0xffff0000, v204
	v_lshlrev_b32_e32 v2, 16, v204
	v_pk_mul_f32 v[10:11], v[10:11], v[2:3]
	v_and_b32_e32 v3, 0xffff0000, v205
	v_lshlrev_b32_e32 v2, 16, v205
	v_pk_mul_f32 v[12:13], v[12:13], v[2:3]
	v_cvt_pk_bf16_f32 v204, v10, v11
	v_cvt_pk_bf16_f32 v205, v12, v13
	global_store_dwordx2 v1, v[204:205], s[74:75] offset:80
	s_waitcnt vmcnt(31)
	v_and_b32_e32 v3, 0xffff0000, v206
	v_lshlrev_b32_e32 v2, 16, v206
	v_pk_mul_f32 v[14:15], v[14:15], v[2:3]
	v_and_b32_e32 v3, 0xffff0000, v207
	v_lshlrev_b32_e32 v2, 16, v207
	v_pk_mul_f32 v[16:17], v[16:17], v[2:3]
	v_cvt_pk_bf16_f32 v206, v14, v15
	v_cvt_pk_bf16_f32 v207, v16, v17
	global_store_dwordx2 v1, v[206:207], s[74:75] offset:96
	s_waitcnt vmcnt(31)
	v_and_b32_e32 v3, 0xffff0000, v208
	v_lshlrev_b32_e32 v2, 16, v208
	v_pk_mul_f32 v[18:19], v[18:19], v[2:3]
	v_and_b32_e32 v3, 0xffff0000, v209
	v_lshlrev_b32_e32 v2, 16, v209
	v_pk_mul_f32 v[20:21], v[20:21], v[2:3]
	v_cvt_pk_bf16_f32 v208, v18, v19
	v_cvt_pk_bf16_f32 v209, v20, v21
	global_store_dwordx2 v1, v[208:209], s[74:75] offset:112
	s_branch .Lgepi_done
.Lgepi_scale:
	global_load_dwordx4 v[210:213], v2, s[0:1]
	global_load_dwordx4 v[214:217], v2, s[0:1] offset:32
	global_load_dwordx4 v[218:221], v2, s[0:1] offset:64
	global_load_dwordx4 v[222:225], v2, s[0:1] offset:96
	global_load_dwordx4 v[226:229], v2, s[0:1] offset:128
	global_load_dwordx4 v[230:233], v2, s[0:1] offset:160
	global_load_dwordx4 v[234:237], v2, s[0:1] offset:192
	global_load_dwordx4 v[134:137], v2, s[0:1] offset:224
	s_add_u32 s74, s70, 0x0
	s_addc_u32 s75, s71, 0
	global_load_dwordx2 v[146:147], v0, s[74:75] nt
	global_load_dwordx2 v[148:149], v0, s[74:75] offset:16 nt
	global_load_dwordx2 v[150:151], v0, s[74:75] offset:32 nt
	global_load_dwordx2 v[152:153], v0, s[74:75] offset:48 nt
	global_load_dwordx2 v[154:155], v0, s[74:75] offset:64 nt
	global_load_dwordx2 v[156:157], v0, s[74:75] offset:80 nt
	global_load_dwordx2 v[158:159], v0, s[74:75] offset:96 nt
	global_load_dwordx2 v[160:161], v0, s[74:75] offset:112 nt
	s_add_u32 s74, s70, 0x14000
	s_addc_u32 s75, s71, 0
	global_load_dwordx2 v[162:163], v0, s[74:75] nt
	global_load_dwordx2 v[164:165], v0, s[74:75] offset:16 nt
	global_load_dwordx2 v[166:167], v0, s[74:75] offset:32 nt
	global_load_dwordx2 v[168:169], v0, s[74:75] offset:48 nt
	global_load_dwordx2 v[170:171], v0, s[74:75] offset:64 nt
	global_load_dwordx2 v[172:173], v0, s[74:75] offset:80 nt
	global_load_dwordx2 v[174:175], v0, s[74:75] offset:96 nt
	global_load_dwordx2 v[176:177], v0, s[74:75] offset:112 nt
	s_add_u32 s74, s70, 0x28000
	s_addc_u32 s75, s71, 0
	global_load_dwordx2 v[178:179], v0, s[74:75] nt
	global_load_dwordx2 v[180:181], v0, s[74:75] offset:16 nt
	global_load_dwordx2 v[182:183], v0, s[74:75] offset:32 nt
	global_load_dwordx2 v[184:185], v0, s[74:75] offset:48 nt
	global_load_dwordx2 v[186:187], v0, s[74:75] offset:64 nt
	global_load_dwordx2 v[188:189], v0, s[74:75] offset:80 nt
	global_load_dwordx2 v[190:191], v0, s[74:75] offset:96 nt
	global_load_dwordx2 v[192:193], v0, s[74:75] offset:112 nt
	s_add_u32 s74, s70, 0x3c000
	s_addc_u32 s75, s71, 0
	global_load_dwordx2 v[194:195], v0, s[74:75] nt
	global_load_dwordx2 v[196:197], v0, s[74:75] offset:16 nt
	global_load_dwordx2 v[198:199], v0, s[74:75] offset:32 nt
	global_load_dwordx2 v[200:201], v0, s[74:75] offset:48 nt
	global_load_dwordx2 v[202:203], v0, s[74:75] offset:64 nt
	global_load_dwordx2 v[204:205], v0, s[74:75] offset:80 nt
	global_load_dwordx2 v[206:207], v0, s[74:75] offset:96 nt
	global_load_dwordx2 v[208:209], v0, s[74:75] offset:112 nt
	s_add_u32 s74, s72, 0x0
	s_addc_u32 s75, s73, 0
	s_waitcnt vmcnt(31)
	v_pk_mul_f32 v[118:119], v[118:119], v[210:211]
	v_pk_mul_f32 v[120:121], v[120:121], v[212:213]
	v_and_b32_e32 v3, 0xffff0000, v146
	v_lshlrev_b32_e32 v2, 16, v146
	v_pk_mul_f32 v[118:119], v[118:119], v[2:3]
	v_and_b32_e32 v3, 0xffff0000, v147
	v_lshlrev_b32_e32 v2, 16, v147
	v_pk_mul_f32 v[120:121], v[120:121], v[2:3]
	v_cvt_pk_bf16_f32 v146, v118, v119
	v_cvt_pk_bf16_f32 v147, v120, v121
	global_store_dwordx2 v1, v[146:147], s[74:75]
	s_waitcnt vmcnt(31)
	v_pk_mul_f32 v[122:123], v[122:123], v[214:215]
	v_pk_mul_f32 v[124:125], v[124:125], v[216:217]
	v_and_b32_e32 v3, 0xffff0000, v148
	v_lshlrev_b32_e32 v2, 16, v148
	v_pk_mul_f32 v[122:123], v[122:123], v[2:3]
	v_and_b32_e32 v3, 0xffff0000, v149
	v_lshlrev_b32_e32 v2, 16, v149
	v_pk_mul_f32 v[124:125], v[124:125], v[2:3]
	v_cvt_pk_bf16_f32 v148, v122, v123
	v_cvt_pk_bf16_f32 v149, v124, v125
	global_store_dwordx2 v1, v[148:149], s[74:75] offset:16
	s_waitcnt vmcnt(31)
	v_pk_mul_f32 v[126:127], v[126:127], v[218:219]
	v_pk_mul_f32 v[128:129], v[128:129], v[220:221]
	v_and_b32_e32 v3, 0xffff0000, v150
	v_lshlrev_b32_e32 v2, 16, v150
	v_pk_mul_f32 v[126:127], v[126:127], v[2:3]
	v_and_b32_e32 v3, 0xffff0000, v151
	v_lshlrev_b32_e32 v2, 16, v151
	v_pk_mul_f32 v[128:129], v[128:129], v[2:3]
	v_cvt_pk_bf16_f32 v150, v126, v127
	v_cvt_pk_bf16_f32 v151, v128, v129
	global_store_dwordx2 v1, v[150:151], s[74:75] offset:32
	s_waitcnt vmcnt(31)
	v_pk_mul_f32 v[130:131], v[130:131], v[222:223]
	v_pk_mul_f32 v[132:133], v[132:133], v[224:225]
	v_and_b32_e32 v3, 0xffff0000, v152
	v_lshlrev_b32_e32 v2, 16, v152
	v_pk_mul_f32 v[130:131], v[130:131], v[2:3]
	v_and_b32_e32 v3, 0xffff0000, v153
	v_lshlrev_b32_e32 v2, 16, v153
	v_pk_mul_f32 v[132:133], v[132:133], v[2:3]
	v_cvt_pk_bf16_f32 v152, v130, v131
	v_cvt_pk_bf16_f32 v153, v132, v133
	global_store_dwordx2 v1, v[152:153], s[74:75] offset:48
	s_waitcnt vmcnt(31)
	v_pk_mul_f32 v[102:103], v[102:103], v[226:227]
	v_pk_mul_f32 v[104:105], v[104:105], v[228:229]
	v_and_b32_e32 v3, 0xffff0000, v154
	v_lshlrev_b32_e32 v2, 16, v154
	v_pk_mul_f32 v[102:103], v[102:103], v[2:3]
	v_and_b32_e32 v3, 0xffff0000, v155
	v_lshlrev_b32_e32 v2, 16, v155
	v_pk_mul_f32 v[104:105], v[104:105], v[2:3]
	v_cvt_pk_bf16_f32 v154, v102, v103
	v_cvt_pk_bf16_f32 v155, v104, v105
	global_store_dwordx2 v1, v[154:155], s[74:75] offset:64
	s_waitcnt vmcnt(31)
	v_pk_mul_f32 v[106:107], v[106:107], v[230:231]
	v_pk_mul_f32 v[108:109], v[108:109], v[232:233]
	v_and_b32_e32 v3, 0xffff0000, v156
	v_lshlrev_b32_e32 v2, 16, v156
	v_pk_mul_f32 v[106:107], v[106:107], v[2:3]
	v_and_b32_e32 v3, 0xffff0000, v157
	v_lshlrev_b32_e32 v2, 16, v157
	v_pk_mul_f32 v[108:109], v[108:109], v[2:3]
	v_cvt_pk_bf16_f32 v156, v106, v107
	v_cvt_pk_bf16_f32 v157, v108, v109
	global_store_dwordx2 v1, v[156:157], s[74:75] offset:80
	s_waitcnt vmcnt(31)
	v_pk_mul_f32 v[110:111], v[110:111], v[234:235]
	v_pk_mul_f32 v[112:113], v[112:113], v[236:237]
	v_and_b32_e32 v3, 0xffff0000, v158
	v_lshlrev_b32_e32 v2, 16, v158
	v_pk_mul_f32 v[110:111], v[110:111], v[2:3]
	v_and_b32_e32 v3, 0xffff0000, v159
	v_lshlrev_b32_e32 v2, 16, v159
	v_pk_mul_f32 v[112:113], v[112:113], v[2:3]
	v_cvt_pk_bf16_f32 v158, v110, v111
	v_cvt_pk_bf16_f32 v159, v112, v113
	global_store_dwordx2 v1, v[158:159], s[74:75] offset:96
	s_waitcnt vmcnt(31)
	v_pk_mul_f32 v[114:115], v[114:115], v[134:135]
	v_pk_mul_f32 v[116:117], v[116:117], v[136:137]
	v_and_b32_e32 v3, 0xffff0000, v160
	v_lshlrev_b32_e32 v2, 16, v160
	v_pk_mul_f32 v[114:115], v[114:115], v[2:3]
	v_and_b32_e32 v3, 0xffff0000, v161
	v_lshlrev_b32_e32 v2, 16, v161
	v_pk_mul_f32 v[116:117], v[116:117], v[2:3]
	v_cvt_pk_bf16_f32 v160, v114, v115
	v_cvt_pk_bf16_f32 v161, v116, v117
	global_store_dwordx2 v1, v[160:161], s[74:75] offset:112
	s_add_u32 s74, s72, 0x10000
	s_addc_u32 s75, s73, 0
	s_waitcnt vmcnt(31)
	v_pk_mul_f32 v[86:87], v[86:87], v[210:211]
	v_pk_mul_f32 v[88:89], v[88:89], v[212:213]
	v_and_b32_e32 v3, 0xffff0000, v162
	v_lshlrev_b32_e32 v2, 16, v162
	v_pk_mul_f32 v[86:87], v[86:87], v[2:3]
	v_and_b32_e32 v3, 0xffff0000, v163
	v_lshlrev_b32_e32 v2, 16, v163
	v_pk_mul_f32 v[88:89], v[88:89], v[2:3]
	v_cvt_pk_bf16_f32 v162, v86, v87
	v_cvt_pk_bf16_f32 v163, v88, v89
	global_store_dwordx2 v1, v[162:163], s[74:75]
	s_waitcnt vmcnt(31)
	v_pk_mul_f32 v[90:91], v[90:91], v[214:215]
	v_pk_mul_f32 v[92:93], v[92:93], v[216:217]
	v_and_b32_e32 v3, 0xffff0000, v164
	v_lshlrev_b32_e32 v2, 16, v164
	v_pk_mul_f32 v[90:91], v[90:91], v[2:3]
	v_and_b32_e32 v3, 0xffff0000, v165
	v_lshlrev_b32_e32 v2, 16, v165
	v_pk_mul_f32 v[92:93], v[92:93], v[2:3]
	v_cvt_pk_bf16_f32 v164, v90, v91
	v_cvt_pk_bf16_f32 v165, v92, v93
	global_store_dwordx2 v1, v[164:165], s[74:75] offset:16
	s_waitcnt vmcnt(31)
	v_pk_mul_f32 v[94:95], v[94:95], v[218:219]
	v_pk_mul_f32 v[96:97], v[96:97], v[220:221]
	v_and_b32_e32 v3, 0xffff0000, v166
	v_lshlrev_b32_e32 v2, 16, v166
	v_pk_mul_f32 v[94:95], v[94:95], v[2:3]
	v_and_b32_e32 v3, 0xffff0000, v167
	v_lshlrev_b32_e32 v2, 16, v167
	v_pk_mul_f32 v[96:97], v[96:97], v[2:3]
	v_cvt_pk_bf16_f32 v166, v94, v95
	v_cvt_pk_bf16_f32 v167, v96, v97
	global_store_dwordx2 v1, v[166:167], s[74:75] offset:32
	s_waitcnt vmcnt(31)
	v_pk_mul_f32 v[98:99], v[98:99], v[222:223]
	v_pk_mul_f32 v[100:101], v[100:101], v[224:225]
	v_and_b32_e32 v3, 0xffff0000, v168
	v_lshlrev_b32_e32 v2, 16, v168
	v_pk_mul_f32 v[98:99], v[98:99], v[2:3]
	v_and_b32_e32 v3, 0xffff0000, v169
	v_lshlrev_b32_e32 v2, 16, v169
	v_pk_mul_f32 v[100:101], v[100:101], v[2:3]
	v_cvt_pk_bf16_f32 v168, v98, v99
	v_cvt_pk_bf16_f32 v169, v100, v101
	global_store_dwordx2 v1, v[168:169], s[74:75] offset:48
	s_waitcnt vmcnt(31)
	v_pk_mul_f32 v[70:71], v[70:71], v[226:227]
	v_pk_mul_f32 v[72:73], v[72:73], v[228:229]
	v_and_b32_e32 v3, 0xffff0000, v170
	v_lshlrev_b32_e32 v2, 16, v170
	v_pk_mul_f32 v[70:71], v[70:71], v[2:3]
	v_and_b32_e32 v3, 0xffff0000, v171
	v_lshlrev_b32_e32 v2, 16, v171
	v_pk_mul_f32 v[72:73], v[72:73], v[2:3]
	v_cvt_pk_bf16_f32 v170, v70, v71
	v_cvt_pk_bf16_f32 v171, v72, v73
	global_store_dwordx2 v1, v[170:171], s[74:75] offset:64
	s_waitcnt vmcnt(31)
	v_pk_mul_f32 v[74:75], v[74:75], v[230:231]
	v_pk_mul_f32 v[76:77], v[76:77], v[232:233]
	v_and_b32_e32 v3, 0xffff0000, v172
	v_lshlrev_b32_e32 v2, 16, v172
	v_pk_mul_f32 v[74:75], v[74:75], v[2:3]
	v_and_b32_e32 v3, 0xffff0000, v173
	v_lshlrev_b32_e32 v2, 16, v173
	v_pk_mul_f32 v[76:77], v[76:77], v[2:3]
	v_cvt_pk_bf16_f32 v172, v74, v75
	v_cvt_pk_bf16_f32 v173, v76, v77
	global_store_dwordx2 v1, v[172:173], s[74:75] offset:80
	s_waitcnt vmcnt(31)
	v_pk_mul_f32 v[78:79], v[78:79], v[234:235]
	v_pk_mul_f32 v[80:81], v[80:81], v[236:237]
	v_and_b32_e32 v3, 0xffff0000, v174
	v_lshlrev_b32_e32 v2, 16, v174
	v_pk_mul_f32 v[78:79], v[78:79], v[2:3]
	v_and_b32_e32 v3, 0xffff0000, v175
	v_lshlrev_b32_e32 v2, 16, v175
	v_pk_mul_f32 v[80:81], v[80:81], v[2:3]
	v_cvt_pk_bf16_f32 v174, v78, v79
	v_cvt_pk_bf16_f32 v175, v80, v81
	global_store_dwordx2 v1, v[174:175], s[74:75] offset:96
	s_waitcnt vmcnt(31)
	v_pk_mul_f32 v[82:83], v[82:83], v[134:135]
	v_pk_mul_f32 v[84:85], v[84:85], v[136:137]
	v_and_b32_e32 v3, 0xffff0000, v176
	v_lshlrev_b32_e32 v2, 16, v176
	v_pk_mul_f32 v[82:83], v[82:83], v[2:3]
	v_and_b32_e32 v3, 0xffff0000, v177
	v_lshlrev_b32_e32 v2, 16, v177
	v_pk_mul_f32 v[84:85], v[84:85], v[2:3]
	v_cvt_pk_bf16_f32 v176, v82, v83
	v_cvt_pk_bf16_f32 v177, v84, v85
	global_store_dwordx2 v1, v[176:177], s[74:75] offset:112
	s_add_u32 s74, s72, 0x20000
	s_addc_u32 s75, s73, 0
	s_waitcnt vmcnt(31)
	v_pk_mul_f32 v[54:55], v[54:55], v[210:211]
	v_pk_mul_f32 v[56:57], v[56:57], v[212:213]
	v_and_b32_e32 v3, 0xffff0000, v178
	v_lshlrev_b32_e32 v2, 16, v178
	v_pk_mul_f32 v[54:55], v[54:55], v[2:3]
	v_and_b32_e32 v3, 0xffff0000, v179
	v_lshlrev_b32_e32 v2, 16, v179
	v_pk_mul_f32 v[56:57], v[56:57], v[2:3]
	v_cvt_pk_bf16_f32 v178, v54, v55
	v_cvt_pk_bf16_f32 v179, v56, v57
	global_store_dwordx2 v1, v[178:179], s[74:75]
	s_waitcnt vmcnt(31)
	v_pk_mul_f32 v[58:59], v[58:59], v[214:215]
	v_pk_mul_f32 v[60:61], v[60:61], v[216:217]
	v_and_b32_e32 v3, 0xffff0000, v180
	v_lshlrev_b32_e32 v2, 16, v180
	v_pk_mul_f32 v[58:59], v[58:59], v[2:3]
	v_and_b32_e32 v3, 0xffff0000, v181
	v_lshlrev_b32_e32 v2, 16, v181
	v_pk_mul_f32 v[60:61], v[60:61], v[2:3]
	v_cvt_pk_bf16_f32 v180, v58, v59
	v_cvt_pk_bf16_f32 v181, v60, v61
	global_store_dwordx2 v1, v[180:181], s[74:75] offset:16
	s_waitcnt vmcnt(31)
	v_pk_mul_f32 v[62:63], v[62:63], v[218:219]
	v_pk_mul_f32 v[64:65], v[64:65], v[220:221]
	v_and_b32_e32 v3, 0xffff0000, v182
	v_lshlrev_b32_e32 v2, 16, v182
	v_pk_mul_f32 v[62:63], v[62:63], v[2:3]
	v_and_b32_e32 v3, 0xffff0000, v183
	v_lshlrev_b32_e32 v2, 16, v183
	v_pk_mul_f32 v[64:65], v[64:65], v[2:3]
	v_cvt_pk_bf16_f32 v182, v62, v63
	v_cvt_pk_bf16_f32 v183, v64, v65
	global_store_dwordx2 v1, v[182:183], s[74:75] offset:32
	s_waitcnt vmcnt(31)
	v_pk_mul_f32 v[66:67], v[66:67], v[222:223]
	v_pk_mul_f32 v[68:69], v[68:69], v[224:225]
	v_and_b32_e32 v3, 0xffff0000, v184
	v_lshlrev_b32_e32 v2, 16, v184
	v_pk_mul_f32 v[66:67], v[66:67], v[2:3]
	v_and_b32_e32 v3, 0xffff0000, v185
	v_lshlrev_b32_e32 v2, 16, v185
	v_pk_mul_f32 v[68:69], v[68:69], v[2:3]
	v_cvt_pk_bf16_f32 v184, v66, v67
	v_cvt_pk_bf16_f32 v185, v68, v69
	global_store_dwordx2 v1, v[184:185], s[74:75] offset:48
	s_waitcnt vmcnt(31)
	v_pk_mul_f32 v[38:39], v[38:39], v[226:227]
	v_pk_mul_f32 v[40:41], v[40:41], v[228:229]
	v_and_b32_e32 v3, 0xffff0000, v186
	v_lshlrev_b32_e32 v2, 16, v186
	v_pk_mul_f32 v[38:39], v[38:39], v[2:3]
	v_and_b32_e32 v3, 0xffff0000, v187
	v_lshlrev_b32_e32 v2, 16, v187
	v_pk_mul_f32 v[40:41], v[40:41], v[2:3]
	v_cvt_pk_bf16_f32 v186, v38, v39
	v_cvt_pk_bf16_f32 v187, v40, v41
	global_store_dwordx2 v1, v[186:187], s[74:75] offset:64
	s_waitcnt vmcnt(31)
	v_pk_mul_f32 v[42:43], v[42:43], v[230:231]
	v_pk_mul_f32 v[44:45], v[44:45], v[232:233]
	v_and_b32_e32 v3, 0xffff0000, v188
	v_lshlrev_b32_e32 v2, 16, v188
	v_pk_mul_f32 v[42:43], v[42:43], v[2:3]
	v_and_b32_e32 v3, 0xffff0000, v189
	v_lshlrev_b32_e32 v2, 16, v189
	v_pk_mul_f32 v[44:45], v[44:45], v[2:3]
	v_cvt_pk_bf16_f32 v188, v42, v43
	v_cvt_pk_bf16_f32 v189, v44, v45
	global_store_dwordx2 v1, v[188:189], s[74:75] offset:80
	s_waitcnt vmcnt(31)
	v_pk_mul_f32 v[46:47], v[46:47], v[234:235]
	v_pk_mul_f32 v[48:49], v[48:49], v[236:237]
	v_and_b32_e32 v3, 0xffff0000, v190
	v_lshlrev_b32_e32 v2, 16, v190
	v_pk_mul_f32 v[46:47], v[46:47], v[2:3]
	v_and_b32_e32 v3, 0xffff0000, v191
	v_lshlrev_b32_e32 v2, 16, v191
	v_pk_mul_f32 v[48:49], v[48:49], v[2:3]
	v_cvt_pk_bf16_f32 v190, v46, v47
	v_cvt_pk_bf16_f32 v191, v48, v49
	global_store_dwordx2 v1, v[190:191], s[74:75] offset:96
	s_waitcnt vmcnt(31)
	v_pk_mul_f32 v[50:51], v[50:51], v[134:135]
	v_pk_mul_f32 v[52:53], v[52:53], v[136:137]
	v_and_b32_e32 v3, 0xffff0000, v192
	v_lshlrev_b32_e32 v2, 16, v192
	v_pk_mul_f32 v[50:51], v[50:51], v[2:3]
	v_and_b32_e32 v3, 0xffff0000, v193
	v_lshlrev_b32_e32 v2, 16, v193
	v_pk_mul_f32 v[52:53], v[52:53], v[2:3]
	v_cvt_pk_bf16_f32 v192, v50, v51
	v_cvt_pk_bf16_f32 v193, v52, v53
	global_store_dwordx2 v1, v[192:193], s[74:75] offset:112
	s_add_u32 s74, s72, 0x30000
	s_addc_u32 s75, s73, 0
	s_waitcnt vmcnt(31)
	v_pk_mul_f32 v[22:23], v[22:23], v[210:211]
	v_pk_mul_f32 v[24:25], v[24:25], v[212:213]
	v_and_b32_e32 v3, 0xffff0000, v194
	v_lshlrev_b32_e32 v2, 16, v194
	v_pk_mul_f32 v[22:23], v[22:23], v[2:3]
	v_and_b32_e32 v3, 0xffff0000, v195
	v_lshlrev_b32_e32 v2, 16, v195
	v_pk_mul_f32 v[24:25], v[24:25], v[2:3]
	v_cvt_pk_bf16_f32 v194, v22, v23
	v_cvt_pk_bf16_f32 v195, v24, v25
	global_store_dwordx2 v1, v[194:195], s[74:75]
	s_waitcnt vmcnt(31)
	v_pk_mul_f32 v[26:27], v[26:27], v[214:215]
	v_pk_mul_f32 v[28:29], v[28:29], v[216:217]
	v_and_b32_e32 v3, 0xffff0000, v196
	v_lshlrev_b32_e32 v2, 16, v196
	v_pk_mul_f32 v[26:27], v[26:27], v[2:3]
	v_and_b32_e32 v3, 0xffff0000, v197
	v_lshlrev_b32_e32 v2, 16, v197
	v_pk_mul_f32 v[28:29], v[28:29], v[2:3]
	v_cvt_pk_bf16_f32 v196, v26, v27
	v_cvt_pk_bf16_f32 v197, v28, v29
	global_store_dwordx2 v1, v[196:197], s[74:75] offset:16
	s_waitcnt vmcnt(31)
	v_pk_mul_f32 v[30:31], v[30:31], v[218:219]
	v_pk_mul_f32 v[32:33], v[32:33], v[220:221]
	v_and_b32_e32 v3, 0xffff0000, v198
	v_lshlrev_b32_e32 v2, 16, v198
	v_pk_mul_f32 v[30:31], v[30:31], v[2:3]
	v_and_b32_e32 v3, 0xffff0000, v199
	v_lshlrev_b32_e32 v2, 16, v199
	v_pk_mul_f32 v[32:33], v[32:33], v[2:3]
	v_cvt_pk_bf16_f32 v198, v30, v31
	v_cvt_pk_bf16_f32 v199, v32, v33
	global_store_dwordx2 v1, v[198:199], s[74:75] offset:32
	s_waitcnt vmcnt(31)
	v_pk_mul_f32 v[34:35], v[34:35], v[222:223]
	v_pk_mul_f32 v[36:37], v[36:37], v[224:225]
	v_and_b32_e32 v3, 0xffff0000, v200
	v_lshlrev_b32_e32 v2, 16, v200
	v_pk_mul_f32 v[34:35], v[34:35], v[2:3]
	v_and_b32_e32 v3, 0xffff0000, v201
	v_lshlrev_b32_e32 v2, 16, v201
	v_pk_mul_f32 v[36:37], v[36:37], v[2:3]
	v_cvt_pk_bf16_f32 v200, v34, v35
	v_cvt_pk_bf16_f32 v201, v36, v37
	global_store_dwordx2 v1, v[200:201], s[74:75] offset:48
	s_waitcnt vmcnt(31)
	v_pk_mul_f32 v[6:7], v[6:7], v[226:227]
	v_pk_mul_f32 v[8:9], v[8:9], v[228:229]
	v_and_b32_e32 v3, 0xffff0000, v202
	v_lshlrev_b32_e32 v2, 16, v202
	v_pk_mul_f32 v[6:7], v[6:7], v[2:3]
	v_and_b32_e32 v3, 0xffff0000, v203
	v_lshlrev_b32_e32 v2, 16, v203
	v_pk_mul_f32 v[8:9], v[8:9], v[2:3]
	v_cvt_pk_bf16_f32 v202, v6, v7
	v_cvt_pk_bf16_f32 v203, v8, v9
	global_store_dwordx2 v1, v[202:203], s[74:75] offset:64
	s_waitcnt vmcnt(31)
	v_pk_mul_f32 v[10:11], v[10:11], v[230:231]
	v_pk_mul_f32 v[12:13], v[12:13], v[232:233]
	v_and_b32_e32 v3, 0xffff0000, v204
	v_lshlrev_b32_e32 v2, 16, v204
	v_pk_mul_f32 v[10:11], v[10:11], v[2:3]
	v_and_b32_e32 v3, 0xffff0000, v205
	v_lshlrev_b32_e32 v2, 16, v205
	v_pk_mul_f32 v[12:13], v[12:13], v[2:3]
	v_cvt_pk_bf16_f32 v204, v10, v11
	v_cvt_pk_bf16_f32 v205, v12, v13
	global_store_dwordx2 v1, v[204:205], s[74:75] offset:80
	s_waitcnt vmcnt(31)
	v_pk_mul_f32 v[14:15], v[14:15], v[234:235]
	v_pk_mul_f32 v[16:17], v[16:17], v[236:237]
	v_and_b32_e32 v3, 0xffff0000, v206
	v_lshlrev_b32_e32 v2, 16, v206
	v_pk_mul_f32 v[14:15], v[14:15], v[2:3]
	v_and_b32_e32 v3, 0xffff0000, v207
	v_lshlrev_b32_e32 v2, 16, v207
	v_pk_mul_f32 v[16:17], v[16:17], v[2:3]
	v_cvt_pk_bf16_f32 v206, v14, v15
	v_cvt_pk_bf16_f32 v207, v16, v17
	global_store_dwordx2 v1, v[206:207], s[74:75] offset:96
	s_waitcnt vmcnt(31)
	v_pk_mul_f32 v[18:19], v[18:19], v[134:135]
	v_pk_mul_f32 v[20:21], v[20:21], v[136:137]
	v_and_b32_e32 v3, 0xffff0000, v208
	v_lshlrev_b32_e32 v2, 16, v208
	v_pk_mul_f32 v[18:19], v[18:19], v[2:3]
	v_and_b32_e32 v3, 0xffff0000, v209
	v_lshlrev_b32_e32 v2, 16, v209
	v_pk_mul_f32 v[20:21], v[20:21], v[2:3]
	v_cvt_pk_bf16_f32 v208, v18, v19
	v_cvt_pk_bf16_f32 v209, v20, v21
	global_store_dwordx2 v1, v[208:209], s[74:75] offset:112

.LBB0_1152:
	s_and_b64 vcc, exec, s[4:5]
	s_cbranch_vccz .LBB0_1154
	v_readlane_b32 s70, v254, 8
	v_readlane_b32 s71, v254, 9
	v_ashrrev_i32_e32 v0, 1, v144
	s_movk_i32 s0, 0xff80
	v_and_or_b32 v0, v0, s0, v161
	v_lshlrev_b32_e32 v2, 6, v145
	v_and_or_b32 v2, v2, s33, v160
	v_add_u32_e32 v2, s68, v2
	v_lshlrev_b32_e32 v0, 1, v0
	v_mad_u32_u24 v1, v2, s92, v0
	v_lshl_add_u32 v3, v2, 11, v0
	s_mov_b64 s[72:73], s[46:47]
	v_mov_b32_e32 v146, 0
	v_mov_b32_e32 v147, 0
	v_mov_b32_e32 v148, 0
	v_mov_b32_e32 v149, 0
	v_mov_b32_e32 v150, 0
	v_mov_b32_e32 v151, 0
	v_mov_b32_e32 v152, 0
	v_mov_b32_e32 v153, 0
	v_mov_b32_e32 v154, 0
	v_mov_b32_e32 v155, 0
	v_mov_b32_e32 v156, 0
	v_mov_b32_e32 v157, 0
	v_mov_b32_e32 v158, 0
	v_mov_b32_e32 v159, 0
	v_mov_b32_e32 v160, 0
	v_mov_b32_e32 v161, 0
	v_mov_b32_e32 v162, 0
	v_mov_b32_e32 v163, 0
	v_mov_b32_e32 v164, 0
	v_mov_b32_e32 v165, 0
	v_mov_b32_e32 v166, 0
	v_mov_b32_e32 v167, 0
	v_mov_b32_e32 v168, 0
	v_mov_b32_e32 v169, 0
	v_mov_b32_e32 v170, 0
	v_mov_b32_e32 v171, 0
	v_mov_b32_e32 v172, 0
	v_mov_b32_e32 v173, 0
	v_mov_b32_e32 v174, 0
	v_mov_b32_e32 v175, 0
	v_mov_b32_e32 v176, 0
	v_mov_b32_e32 v177, 0
	global_load_short_d16_hi v146, v1, s[70:71] nt
	global_load_short_d16_hi v147, v1, s[70:71] offset:64 nt
	global_load_short_d16_hi v148, v1, s[70:71] offset:128 nt
	global_load_short_d16_hi v149, v1, s[70:71] offset:192 nt
	s_add_u32 s70, s70, 0x28000
	s_addc_u32 s71, s71, 0
	global_load_short_d16_hi v150, v1, s[70:71] nt
	global_load_short_d16_hi v151, v1, s[70:71] offset:64 nt
	global_load_short_d16_hi v152, v1, s[70:71] offset:128 nt
	global_load_short_d16_hi v153, v1, s[70:71] offset:192 nt
	s_add_u32 s70, s70, 0x28000
	s_addc_u32 s71, s71, 0
	global_load_short_d16_hi v154, v1, s[70:71] nt
	global_load_short_d16_hi v155, v1, s[70:71] offset:64 nt
	global_load_short_d16_hi v156, v1, s[70:71] offset:128 nt
	global_load_short_d16_hi v157, v1, s[70:71] offset:192 nt
	s_add_u32 s70, s70, 0x28000
	s_addc_u32 s71, s71, 0
	global_load_short_d16_hi v158, v1, s[70:71] nt
	global_load_short_d16_hi v159, v1, s[70:71] offset:64 nt
	global_load_short_d16_hi v160, v1, s[70:71] offset:128 nt
	global_load_short_d16_hi v161, v1, s[70:71] offset:192 nt
	s_add_u32 s70, s70, 0xc8000
	s_addc_u32 s71, s71, 0
	global_load_short_d16_hi v162, v1, s[70:71] nt
	global_load_short_d16_hi v163, v1, s[70:71] offset:64 nt
	global_load_short_d16_hi v164, v1, s[70:71] offset:128 nt
	global_load_short_d16_hi v165, v1, s[70:71] offset:192 nt
	s_add_u32 s70, s70, 0x28000
	s_addc_u32 s71, s71, 0
	global_load_short_d16_hi v166, v1, s[70:71] nt
	global_load_short_d16_hi v167, v1, s[70:71] offset:64 nt
	global_load_short_d16_hi v168, v1, s[70:71] offset:128 nt
	global_load_short_d16_hi v169, v1, s[70:71] offset:192 nt
	s_add_u32 s70, s70, 0x28000
	s_addc_u32 s71, s71, 0
	global_load_short_d16_hi v170, v1, s[70:71] nt
	global_load_short_d16_hi v171, v1, s[70:71] offset:64 nt
	global_load_short_d16_hi v172, v1, s[70:71] offset:128 nt
	global_load_short_d16_hi v173, v1, s[70:71] offset:192 nt
	s_add_u32 s70, s70, 0x28000
	s_addc_u32 s71, s71, 0
	global_load_short_d16_hi v174, v1, s[70:71] nt
	global_load_short_d16_hi v175, v1, s[70:71] offset:64 nt
	global_load_short_d16_hi v176, v1, s[70:71] offset:128 nt
	global_load_short_d16_hi v177, v1, s[70:71] offset:192 nt
	s_add_u32 s70, s70, 0xc8000
	s_addc_u32 s71, s71, 0
	s_waitcnt vmcnt(16)
	v_mul_f32_e32 v178, v118, v146
	v_cvt_pk_bf16_f32 v178, v178, v178
	global_store_short v3, v178, s[72:73]
	v_mul_f32_e32 v179, v86, v147
	v_cvt_pk_bf16_f32 v179, v179, v179
	global_store_short v3, v179, s[72:73] offset:64
	v_mul_f32_e32 v180, v54, v148
	v_cvt_pk_bf16_f32 v180, v180, v180
	global_store_short v3, v180, s[72:73] offset:128
	v_mul_f32_e32 v181, v22, v149
	v_cvt_pk_bf16_f32 v181, v181, v181
	global_store_short v3, v181, s[72:73] offset:192
	s_add_u32 s72, s72, 0x20000
	s_addc_u32 s73, s73, 0
	v_mul_f32_e32 v178, v119, v150
	v_cvt_pk_bf16_f32 v178, v178, v178
	global_store_short v3, v178, s[72:73]
	v_mul_f32_e32 v179, v87, v151
	v_cvt_pk_bf16_f32 v179, v179, v179
	global_store_short v3, v179, s[72:73] offset:64
	v_mul_f32_e32 v180, v55, v152
	v_cvt_pk_bf16_f32 v180, v180, v180
	global_store_short v3, v180, s[72:73] offset:128
	v_mul_f32_e32 v181, v23, v153
	v_cvt_pk_bf16_f32 v181, v181, v181
	global_store_short v3, v181, s[72:73] offset:192
	s_add_u32 s72, s72, 0x20000
	s_addc_u32 s73, s73, 0
	v_mul_f32_e32 v178, v120, v154
	v_cvt_pk_bf16_f32 v178, v178, v178
	global_store_short v3, v178, s[72:73]
	v_mul_f32_e32 v179, v88, v155
	v_cvt_pk_bf16_f32 v179, v179, v179
	global_store_short v3, v179, s[72:73] offset:64
	v_mul_f32_e32 v180, v56, v156
	v_cvt_pk_bf16_f32 v180, v180, v180
	global_store_short v3, v180, s[72:73] offset:128
	v_mul_f32_e32 v181, v24, v157
	v_cvt_pk_bf16_f32 v181, v181, v181
	global_store_short v3, v181, s[72:73] offset:192
	s_add_u32 s72, s72, 0x20000
	s_addc_u32 s73, s73, 0
	v_mul_f32_e32 v178, v121, v158
	v_cvt_pk_bf16_f32 v178, v178, v178
	global_store_short v3, v178, s[72:73]
	v_mul_f32_e32 v179, v89, v159
	v_cvt_pk_bf16_f32 v179, v179, v179
	global_store_short v3, v179, s[72:73] offset:64
	v_mul_f32_e32 v180, v57, v160
	v_cvt_pk_bf16_f32 v180, v180, v180
	global_store_short v3, v180, s[72:73] offset:128
	v_mul_f32_e32 v181, v25, v161
	v_cvt_pk_bf16_f32 v181, v181, v181
	global_store_short v3, v181, s[72:73] offset:192
	s_add_u32 s72, s72, 0xa0000
	s_addc_u32 s73, s73, 0
	global_load_short_d16_hi v146, v1, s[70:71] nt
	global_load_short_d16_hi v147, v1, s[70:71] offset:64 nt
	global_load_short_d16_hi v148, v1, s[70:71] offset:128 nt
	global_load_short_d16_hi v149, v1, s[70:71] offset:192 nt
	s_add_u32 s70, s70, 0x28000
	s_addc_u32 s71, s71, 0
	global_load_short_d16_hi v150, v1, s[70:71] nt
	global_load_short_d16_hi v151, v1, s[70:71] offset:64 nt
	global_load_short_d16_hi v152, v1, s[70:71] offset:128 nt
	global_load_short_d16_hi v153, v1, s[70:71] offset:192 nt
	s_add_u32 s70, s70, 0x28000
	s_addc_u32 s71, s71, 0
	global_load_short_d16_hi v154, v1, s[70:71] nt
	global_load_short_d16_hi v155, v1, s[70:71] offset:64 nt
	global_load_short_d16_hi v156, v1, s[70:71] offset:128 nt
	global_load_short_d16_hi v157, v1, s[70:71] offset:192 nt
	s_add_u32 s70, s70, 0x28000
	s_addc_u32 s71, s71, 0
	global_load_short_d16_hi v158, v1, s[70:71] nt
	global_load_short_d16_hi v159, v1, s[70:71] offset:64 nt
	global_load_short_d16_hi v160, v1, s[70:71] offset:128 nt
	global_load_short_d16_hi v161, v1, s[70:71] offset:192 nt
	s_add_u32 s70, s70, 0xc8000
	s_addc_u32 s71, s71, 0
	s_waitcnt vmcnt(32)
	v_mul_f32_e32 v178, v122, v162
	v_cvt_pk_bf16_f32 v178, v178, v178
	global_store_short v3, v178, s[72:73]
	v_mul_f32_e32 v179, v90, v163
	v_cvt_pk_bf16_f32 v179, v179, v179
	global_store_short v3, v179, s[72:73] offset:64
	v_mul_f32_e32 v180, v58, v164
	v_cvt_pk_bf16_f32 v180, v180, v180
	global_store_short v3, v180, s[72:73] offset:128
	v_mul_f32_e32 v181, v26, v165
	v_cvt_pk_bf16_f32 v181, v181, v181
	global_store_short v3, v181, s[72:73] offset:192
	s_add_u32 s72, s72, 0x20000
	s_addc_u32 s73, s73, 0
	v_mul_f32_e32 v178, v123, v166
	v_cvt_pk_bf16_f32 v178, v178, v178
	global_store_short v3, v178, s[72:73]
	v_mul_f32_e32 v179, v91, v167
	v_cvt_pk_bf16_f32 v179, v179, v179
	global_store_short v3, v179, s[72:73] offset:64
	v_mul_f32_e32 v180, v59, v168
	v_cvt_pk_bf16_f32 v180, v180, v180
	global_store_short v3, v180, s[72:73] offset:128
	v_mul_f32_e32 v181, v27, v169
	v_cvt_pk_bf16_f32 v181, v181, v181
	global_store_short v3, v181, s[72:73] offset:192
	s_add_u32 s72, s72, 0x20000
	s_addc_u32 s73, s73, 0
	v_mul_f32_e32 v178, v124, v170
	v_cvt_pk_bf16_f32 v178, v178, v178
	global_store_short v3, v178, s[72:73]
	v_mul_f32_e32 v179, v92, v171
	v_cvt_pk_bf16_f32 v179, v179, v179
	global_store_short v3, v179, s[72:73] offset:64
	v_mul_f32_e32 v180, v60, v172
	v_cvt_pk_bf16_f32 v180, v180, v180
	global_store_short v3, v180, s[72:73] offset:128
	v_mul_f32_e32 v181, v28, v173
	v_cvt_pk_bf16_f32 v181, v181, v181
	global_store_short v3, v181, s[72:73] offset:192
	s_add_u32 s72, s72, 0x20000
	s_addc_u32 s73, s73, 0
	v_mul_f32_e32 v178, v125, v174
	v_cvt_pk_bf16_f32 v178, v178, v178
	global_store_short v3, v178, s[72:73]
	v_mul_f32_e32 v179, v93, v175
	v_cvt_pk_bf16_f32 v179, v179, v179
	global_store_short v3, v179, s[72:73] offset:64
	v_mul_f32_e32 v180, v61, v176
	v_cvt_pk_bf16_f32 v180, v180, v180
	global_store_short v3, v180, s[72:73] offset:128
	v_mul_f32_e32 v181, v29, v177
	v_cvt_pk_bf16_f32 v181, v181, v181
	global_store_short v3, v181, s[72:73] offset:192
	s_add_u32 s72, s72, 0xa0000
	s_addc_u32 s73, s73, 0
	global_load_short_d16_hi v162, v1, s[70:71] nt
	global_load_short_d16_hi v163, v1, s[70:71] offset:64 nt
	global_load_short_d16_hi v164, v1, s[70:71] offset:128 nt
	global_load_short_d16_hi v165, v1, s[70:71] offset:192 nt
	s_add_u32 s70, s70, 0x28000
	s_addc_u32 s71, s71, 0
	global_load_short_d16_hi v166, v1, s[70:71] nt
	global_load_short_d16_hi v167, v1, s[70:71] offset:64 nt
	global_load_short_d16_hi v168, v1, s[70:71] offset:128 nt
	global_load_short_d16_hi v169, v1, s[70:71] offset:192 nt
	s_add_u32 s70, s70, 0x28000
	s_addc_u32 s71, s71, 0
	global_load_short_d16_hi v170, v1, s[70:71] nt
	global_load_short_d16_hi v171, v1, s[70:71] offset:64 nt
	global_load_short_d16_hi v172, v1, s[70:71] offset:128 nt
	global_load_short_d16_hi v173, v1, s[70:71] offset:192 nt
	s_add_u32 s70, s70, 0x28000
	s_addc_u32 s71, s71, 0
	global_load_short_d16_hi v174, v1, s[70:71] nt
	global_load_short_d16_hi v175, v1, s[70:71] offset:64 nt
	global_load_short_d16_hi v176, v1, s[70:71] offset:128 nt
	global_load_short_d16_hi v177, v1, s[70:71] offset:192 nt
	s_add_u32 s70, s70, 0xc8000
	s_addc_u32 s71, s71, 0
	s_waitcnt vmcnt(32)
	v_mul_f32_e32 v178, v126, v146
	v_cvt_pk_bf16_f32 v178, v178, v178
	global_store_short v3, v178, s[72:73]
	v_mul_f32_e32 v179, v94, v147
	v_cvt_pk_bf16_f32 v179, v179, v179
	global_store_short v3, v179, s[72:73] offset:64
	v_mul_f32_e32 v180, v62, v148
	v_cvt_pk_bf16_f32 v180, v180, v180
	global_store_short v3, v180, s[72:73] offset:128
	v_mul_f32_e32 v181, v30, v149
	v_cvt_pk_bf16_f32 v181, v181, v181
	global_store_short v3, v181, s[72:73] offset:192
	s_add_u32 s72, s72, 0x20000
	s_addc_u32 s73, s73, 0
	v_mul_f32_e32 v178, v127, v150
	v_cvt_pk_bf16_f32 v178, v178, v178
	global_store_short v3, v178, s[72:73]
	v_mul_f32_e32 v179, v95, v151
	v_cvt_pk_bf16_f32 v179, v179, v179
	global_store_short v3, v179, s[72:73] offset:64
	v_mul_f32_e32 v180, v63, v152
	v_cvt_pk_bf16_f32 v180, v180, v180
	global_store_short v3, v180, s[72:73] offset:128
	v_mul_f32_e32 v181, v31, v153
	v_cvt_pk_bf16_f32 v181, v181, v181
	global_store_short v3, v181, s[72:73] offset:192
	s_add_u32 s72, s72, 0x20000
	s_addc_u32 s73, s73, 0
	v_mul_f32_e32 v178, v128, v154
	v_cvt_pk_bf16_f32 v178, v178, v178
	global_store_short v3, v178, s[72:73]
	v_mul_f32_e32 v179, v96, v155
	v_cvt_pk_bf16_f32 v179, v179, v179
	global_store_short v3, v179, s[72:73] offset:64
	v_mul_f32_e32 v180, v64, v156
	v_cvt_pk_bf16_f32 v180, v180, v180
	global_store_short v3, v180, s[72:73] offset:128
	v_mul_f32_e32 v181, v32, v157
	v_cvt_pk_bf16_f32 v181, v181, v181
	global_store_short v3, v181, s[72:73] offset:192
	s_add_u32 s72, s72, 0x20000
	s_addc_u32 s73, s73, 0
	v_mul_f32_e32 v178, v129, v158
	v_cvt_pk_bf16_f32 v178, v178, v178
	global_store_short v3, v178, s[72:73]
	v_mul_f32_e32 v179, v97, v159
	v_cvt_pk_bf16_f32 v179, v179, v179
	global_store_short v3, v179, s[72:73] offset:64
	v_mul_f32_e32 v180, v65, v160
	v_cvt_pk_bf16_f32 v180, v180, v180
	global_store_short v3, v180, s[72:73] offset:128
	v_mul_f32_e32 v181, v33, v161
	v_cvt_pk_bf16_f32 v181, v181, v181
	global_store_short v3, v181, s[72:73] offset:192
	s_add_u32 s72, s72, 0xa0000
	s_addc_u32 s73, s73, 0
	global_load_short_d16_hi v146, v1, s[70:71] nt
	global_load_short_d16_hi v147, v1, s[70:71] offset:64 nt
	global_load_short_d16_hi v148, v1, s[70:71] offset:128 nt
	global_load_short_d16_hi v149, v1, s[70:71] offset:192 nt
	s_add_u32 s70, s70, 0x28000
	s_addc_u32 s71, s71, 0
	global_load_short_d16_hi v150, v1, s[70:71] nt
	global_load_short_d16_hi v151, v1, s[70:71] offset:64 nt
	global_load_short_d16_hi v152, v1, s[70:71] offset:128 nt
	global_load_short_d16_hi v153, v1, s[70:71] offset:192 nt
	s_add_u32 s70, s70, 0x28000
	s_addc_u32 s71, s71, 0
	global_load_short_d16_hi v154, v1, s[70:71] nt
	global_load_short_d16_hi v155, v1, s[70:71] offset:64 nt
	global_load_short_d16_hi v156, v1, s[70:71] offset:128 nt
	global_load_short_d16_hi v157, v1, s[70:71] offset:192 nt
	s_add_u32 s70, s70, 0x28000
	s_addc_u32 s71, s71, 0
	global_load_short_d16_hi v158, v1, s[70:71] nt
	global_load_short_d16_hi v159, v1, s[70:71] offset:64 nt
	global_load_short_d16_hi v160, v1, s[70:71] offset:128 nt
	global_load_short_d16_hi v161, v1, s[70:71] offset:192 nt
	s_add_u32 s70, s70, 0xc8000
	s_addc_u32 s71, s71, 0
	s_waitcnt vmcnt(32)
	v_mul_f32_e32 v178, v130, v162
	v_cvt_pk_bf16_f32 v178, v178, v178
	global_store_short v3, v178, s[72:73]
	v_mul_f32_e32 v179, v98, v163
	v_cvt_pk_bf16_f32 v179, v179, v179
	global_store_short v3, v179, s[72:73] offset:64
	v_mul_f32_e32 v180, v66, v164
	v_cvt_pk_bf16_f32 v180, v180, v180
	global_store_short v3, v180, s[72:73] offset:128
	v_mul_f32_e32 v181, v34, v165
	v_cvt_pk_bf16_f32 v181, v181, v181
	global_store_short v3, v181, s[72:73] offset:192
	s_add_u32 s72, s72, 0x20000
	s_addc_u32 s73, s73, 0
	v_mul_f32_e32 v178, v131, v166
	v_cvt_pk_bf16_f32 v178, v178, v178
	global_store_short v3, v178, s[72:73]
	v_mul_f32_e32 v179, v99, v167
	v_cvt_pk_bf16_f32 v179, v179, v179
	global_store_short v3, v179, s[72:73] offset:64
	v_mul_f32_e32 v180, v67, v168
	v_cvt_pk_bf16_f32 v180, v180, v180
	global_store_short v3, v180, s[72:73] offset:128
	v_mul_f32_e32 v181, v35, v169
	v_cvt_pk_bf16_f32 v181, v181, v181
	global_store_short v3, v181, s[72:73] offset:192
	s_add_u32 s72, s72, 0x20000
	s_addc_u32 s73, s73, 0
	v_mul_f32_e32 v178, v132, v170
	v_cvt_pk_bf16_f32 v178, v178, v178
	global_store_short v3, v178, s[72:73]
	v_mul_f32_e32 v179, v100, v171
	v_cvt_pk_bf16_f32 v179, v179, v179
	global_store_short v3, v179, s[72:73] offset:64
	v_mul_f32_e32 v180, v68, v172
	v_cvt_pk_bf16_f32 v180, v180, v180
	global_store_short v3, v180, s[72:73] offset:128
	v_mul_f32_e32 v181, v36, v173
	v_cvt_pk_bf16_f32 v181, v181, v181
	global_store_short v3, v181, s[72:73] offset:192
	s_add_u32 s72, s72, 0x20000
	s_addc_u32 s73, s73, 0
	v_mul_f32_e32 v178, v133, v174
	v_cvt_pk_bf16_f32 v178, v178, v178
	global_store_short v3, v178, s[72:73]
	v_mul_f32_e32 v179, v101, v175
	v_cvt_pk_bf16_f32 v179, v179, v179
	global_store_short v3, v179, s[72:73] offset:64
	v_mul_f32_e32 v180, v69, v176
	v_cvt_pk_bf16_f32 v180, v180, v180
	global_store_short v3, v180, s[72:73] offset:128
	v_mul_f32_e32 v181, v37, v177
	v_cvt_pk_bf16_f32 v181, v181, v181
	global_store_short v3, v181, s[72:73] offset:192
	s_add_u32 s72, s72, 0xa0000
	s_addc_u32 s73, s73, 0
	global_load_short_d16_hi v162, v1, s[70:71] nt
	global_load_short_d16_hi v163, v1, s[70:71] offset:64 nt
	global_load_short_d16_hi v164, v1, s[70:71] offset:128 nt
	global_load_short_d16_hi v165, v1, s[70:71] offset:192 nt
	s_add_u32 s70, s70, 0x28000
	s_addc_u32 s71, s71, 0
	global_load_short_d16_hi v166, v1, s[70:71] nt
	global_load_short_d16_hi v167, v1, s[70:71] offset:64 nt
	global_load_short_d16_hi v168, v1, s[70:71] offset:128 nt
	global_load_short_d16_hi v169, v1, s[70:71] offset:192 nt
	s_add_u32 s70, s70, 0x28000
	s_addc_u32 s71, s71, 0
	global_load_short_d16_hi v170, v1, s[70:71] nt
	global_load_short_d16_hi v171, v1, s[70:71] offset:64 nt
	global_load_short_d16_hi v172, v1, s[70:71] offset:128 nt
	global_load_short_d16_hi v173, v1, s[70:71] offset:192 nt
	s_add_u32 s70, s70, 0x28000
	s_addc_u32 s71, s71, 0
	global_load_short_d16_hi v174, v1, s[70:71] nt
	global_load_short_d16_hi v175, v1, s[70:71] offset:64 nt
	global_load_short_d16_hi v176, v1, s[70:71] offset:128 nt
	global_load_short_d16_hi v177, v1, s[70:71] offset:192 nt
	s_add_u32 s70, s70, 0xc8000
	s_addc_u32 s71, s71, 0
	s_waitcnt vmcnt(32)
	v_mul_f32_e32 v178, v102, v146
	v_cvt_pk_bf16_f32 v178, v178, v178
	global_store_short v3, v178, s[72:73]
	v_mul_f32_e32 v179, v70, v147
	v_cvt_pk_bf16_f32 v179, v179, v179
	global_store_short v3, v179, s[72:73] offset:64
	v_mul_f32_e32 v180, v38, v148
	v_cvt_pk_bf16_f32 v180, v180, v180
	global_store_short v3, v180, s[72:73] offset:128
	v_mul_f32_e32 v181, v6, v149
	v_cvt_pk_bf16_f32 v181, v181, v181
	global_store_short v3, v181, s[72:73] offset:192
	s_add_u32 s72, s72, 0x20000
	s_addc_u32 s73, s73, 0
	v_mul_f32_e32 v178, v103, v150
	v_cvt_pk_bf16_f32 v178, v178, v178
	global_store_short v3, v178, s[72:73]
	v_mul_f32_e32 v179, v71, v151
	v_cvt_pk_bf16_f32 v179, v179, v179
	global_store_short v3, v179, s[72:73] offset:64
	v_mul_f32_e32 v180, v39, v152
	v_cvt_pk_bf16_f32 v180, v180, v180
	global_store_short v3, v180, s[72:73] offset:128
	v_mul_f32_e32 v181, v7, v153
	v_cvt_pk_bf16_f32 v181, v181, v181
	global_store_short v3, v181, s[72:73] offset:192
	s_add_u32 s72, s72, 0x20000
	s_addc_u32 s73, s73, 0
	v_mul_f32_e32 v178, v104, v154
	v_cvt_pk_bf16_f32 v178, v178, v178
	global_store_short v3, v178, s[72:73]
	v_mul_f32_e32 v179, v72, v155
	v_cvt_pk_bf16_f32 v179, v179, v179
	global_store_short v3, v179, s[72:73] offset:64
	v_mul_f32_e32 v180, v40, v156
	v_cvt_pk_bf16_f32 v180, v180, v180
	global_store_short v3, v180, s[72:73] offset:128
	v_mul_f32_e32 v181, v8, v157
	v_cvt_pk_bf16_f32 v181, v181, v181
	global_store_short v3, v181, s[72:73] offset:192
	s_add_u32 s72, s72, 0x20000
	s_addc_u32 s73, s73, 0
	v_mul_f32_e32 v178, v105, v158
	v_cvt_pk_bf16_f32 v178, v178, v178
	global_store_short v3, v178, s[72:73]
	v_mul_f32_e32 v179, v73, v159
	v_cvt_pk_bf16_f32 v179, v179, v179
	global_store_short v3, v179, s[72:73] offset:64
	v_mul_f32_e32 v180, v41, v160
	v_cvt_pk_bf16_f32 v180, v180, v180
	global_store_short v3, v180, s[72:73] offset:128
	v_mul_f32_e32 v181, v9, v161
	v_cvt_pk_bf16_f32 v181, v181, v181
	global_store_short v3, v181, s[72:73] offset:192
	s_add_u32 s72, s72, 0xa0000
	s_addc_u32 s73, s73, 0
	global_load_short_d16_hi v146, v1, s[70:71] nt
	global_load_short_d16_hi v147, v1, s[70:71] offset:64 nt
	global_load_short_d16_hi v148, v1, s[70:71] offset:128 nt
	global_load_short_d16_hi v149, v1, s[70:71] offset:192 nt
	s_add_u32 s70, s70, 0x28000
	s_addc_u32 s71, s71, 0
	global_load_short_d16_hi v150, v1, s[70:71] nt
	global_load_short_d16_hi v151, v1, s[70:71] offset:64 nt
	global_load_short_d16_hi v152, v1, s[70:71] offset:128 nt
	global_load_short_d16_hi v153, v1, s[70:71] offset:192 nt
	s_add_u32 s70, s70, 0x28000
	s_addc_u32 s71, s71, 0
	global_load_short_d16_hi v154, v1, s[70:71] nt
	global_load_short_d16_hi v155, v1, s[70:71] offset:64 nt
	global_load_short_d16_hi v156, v1, s[70:71] offset:128 nt
	global_load_short_d16_hi v157, v1, s[70:71] offset:192 nt
	s_add_u32 s70, s70, 0x28000
	s_addc_u32 s71, s71, 0
	global_load_short_d16_hi v158, v1, s[70:71] nt
	global_load_short_d16_hi v159, v1, s[70:71] offset:64 nt
	global_load_short_d16_hi v160, v1, s[70:71] offset:128 nt
	global_load_short_d16_hi v161, v1, s[70:71] offset:192 nt
	s_add_u32 s70, s70, 0xc8000
	s_addc_u32 s71, s71, 0
	s_waitcnt vmcnt(32)
	v_mul_f32_e32 v178, v106, v162
	v_cvt_pk_bf16_f32 v178, v178, v178
	global_store_short v3, v178, s[72:73]
	v_mul_f32_e32 v179, v74, v163
	v_cvt_pk_bf16_f32 v179, v179, v179
	global_store_short v3, v179, s[72:73] offset:64
	v_mul_f32_e32 v180, v42, v164
	v_cvt_pk_bf16_f32 v180, v180, v180
	global_store_short v3, v180, s[72:73] offset:128
	v_mul_f32_e32 v181, v10, v165
	v_cvt_pk_bf16_f32 v181, v181, v181
	global_store_short v3, v181, s[72:73] offset:192
	s_add_u32 s72, s72, 0x20000
	s_addc_u32 s73, s73, 0
	v_mul_f32_e32 v178, v107, v166
	v_cvt_pk_bf16_f32 v178, v178, v178
	global_store_short v3, v178, s[72:73]
	v_mul_f32_e32 v179, v75, v167
	v_cvt_pk_bf16_f32 v179, v179, v179
	global_store_short v3, v179, s[72:73] offset:64
	v_mul_f32_e32 v180, v43, v168
	v_cvt_pk_bf16_f32 v180, v180, v180
	global_store_short v3, v180, s[72:73] offset:128
	v_mul_f32_e32 v181, v11, v169
	v_cvt_pk_bf16_f32 v181, v181, v181
	global_store_short v3, v181, s[72:73] offset:192
	s_add_u32 s72, s72, 0x20000
	s_addc_u32 s73, s73, 0
	v_mul_f32_e32 v178, v108, v170
	v_cvt_pk_bf16_f32 v178, v178, v178
	global_store_short v3, v178, s[72:73]
	v_mul_f32_e32 v179, v76, v171
	v_cvt_pk_bf16_f32 v179, v179, v179
	global_store_short v3, v179, s[72:73] offset:64
	v_mul_f32_e32 v180, v44, v172
	v_cvt_pk_bf16_f32 v180, v180, v180
	global_store_short v3, v180, s[72:73] offset:128
	v_mul_f32_e32 v181, v12, v173
	v_cvt_pk_bf16_f32 v181, v181, v181
	global_store_short v3, v181, s[72:73] offset:192
	s_add_u32 s72, s72, 0x20000
	s_addc_u32 s73, s73, 0
	v_mul_f32_e32 v178, v109, v174
	v_cvt_pk_bf16_f32 v178, v178, v178
	global_store_short v3, v178, s[72:73]
	v_mul_f32_e32 v179, v77, v175
	v_cvt_pk_bf16_f32 v179, v179, v179
	global_store_short v3, v179, s[72:73] offset:64
	v_mul_f32_e32 v180, v45, v176
	v_cvt_pk_bf16_f32 v180, v180, v180
	global_store_short v3, v180, s[72:73] offset:128
	v_mul_f32_e32 v181, v13, v177
	v_cvt_pk_bf16_f32 v181, v181, v181
	global_store_short v3, v181, s[72:73] offset:192
	s_add_u32 s72, s72, 0xa0000
	s_addc_u32 s73, s73, 0
	global_load_short_d16_hi v162, v1, s[70:71] nt
	global_load_short_d16_hi v163, v1, s[70:71] offset:64 nt
	global_load_short_d16_hi v164, v1, s[70:71] offset:128 nt
	global_load_short_d16_hi v165, v1, s[70:71] offset:192 nt
	s_add_u32 s70, s70, 0x28000
	s_addc_u32 s71, s71, 0
	global_load_short_d16_hi v166, v1, s[70:71] nt
	global_load_short_d16_hi v167, v1, s[70:71] offset:64 nt
	global_load_short_d16_hi v168, v1, s[70:71] offset:128 nt
	global_load_short_d16_hi v169, v1, s[70:71] offset:192 nt
	s_add_u32 s70, s70, 0x28000
	s_addc_u32 s71, s71, 0
	global_load_short_d16_hi v170, v1, s[70:71] nt
	global_load_short_d16_hi v171, v1, s[70:71] offset:64 nt
	global_load_short_d16_hi v172, v1, s[70:71] offset:128 nt
	global_load_short_d16_hi v173, v1, s[70:71] offset:192 nt
	s_add_u32 s70, s70, 0x28000
	s_addc_u32 s71, s71, 0
	global_load_short_d16_hi v174, v1, s[70:71] nt
	global_load_short_d16_hi v175, v1, s[70:71] offset:64 nt
	global_load_short_d16_hi v176, v1, s[70:71] offset:128 nt
	global_load_short_d16_hi v177, v1, s[70:71] offset:192 nt
	s_waitcnt vmcnt(32)
	v_mul_f32_e32 v178, v110, v146
	v_cvt_pk_bf16_f32 v178, v178, v178
	global_store_short v3, v178, s[72:73]
	v_mul_f32_e32 v179, v78, v147
	v_cvt_pk_bf16_f32 v179, v179, v179
	global_store_short v3, v179, s[72:73] offset:64
	v_mul_f32_e32 v180, v46, v148
	v_cvt_pk_bf16_f32 v180, v180, v180
	global_store_short v3, v180, s[72:73] offset:128
	v_mul_f32_e32 v181, v14, v149
	v_cvt_pk_bf16_f32 v181, v181, v181
	global_store_short v3, v181, s[72:73] offset:192
	s_add_u32 s72, s72, 0x20000
	s_addc_u32 s73, s73, 0
	v_mul_f32_e32 v178, v111, v150
	v_cvt_pk_bf16_f32 v178, v178, v178
	global_store_short v3, v178, s[72:73]
	v_mul_f32_e32 v179, v79, v151
	v_cvt_pk_bf16_f32 v179, v179, v179
	global_store_short v3, v179, s[72:73] offset:64
	v_mul_f32_e32 v180, v47, v152
	v_cvt_pk_bf16_f32 v180, v180, v180
	global_store_short v3, v180, s[72:73] offset:128
	v_mul_f32_e32 v181, v15, v153
	v_cvt_pk_bf16_f32 v181, v181, v181
	global_store_short v3, v181, s[72:73] offset:192
	s_add_u32 s72, s72, 0x20000
	s_addc_u32 s73, s73, 0
	v_mul_f32_e32 v178, v112, v154
	v_cvt_pk_bf16_f32 v178, v178, v178
	global_store_short v3, v178, s[72:73]
	v_mul_f32_e32 v179, v80, v155
	v_cvt_pk_bf16_f32 v179, v179, v179
	global_store_short v3, v179, s[72:73] offset:64
	v_mul_f32_e32 v180, v48, v156
	v_cvt_pk_bf16_f32 v180, v180, v180
	global_store_short v3, v180, s[72:73] offset:128
	v_mul_f32_e32 v181, v16, v157
	v_cvt_pk_bf16_f32 v181, v181, v181
	global_store_short v3, v181, s[72:73] offset:192
	s_add_u32 s72, s72, 0x20000
	s_addc_u32 s73, s73, 0
	v_mul_f32_e32 v178, v113, v158
	v_cvt_pk_bf16_f32 v178, v178, v178
	global_store_short v3, v178, s[72:73]
	v_mul_f32_e32 v179, v81, v159
	v_cvt_pk_bf16_f32 v179, v179, v179
	global_store_short v3, v179, s[72:73] offset:64
	v_mul_f32_e32 v180, v49, v160
	v_cvt_pk_bf16_f32 v180, v180, v180
	global_store_short v3, v180, s[72:73] offset:128
	v_mul_f32_e32 v181, v17, v161
	v_cvt_pk_bf16_f32 v181, v181, v181
	global_store_short v3, v181, s[72:73] offset:192
	s_add_u32 s72, s72, 0xa0000
	s_addc_u32 s73, s73, 0
	s_waitcnt vmcnt(16)
	v_mul_f32_e32 v178, v114, v162
	v_cvt_pk_bf16_f32 v178, v178, v178
	global_store_short v3, v178, s[72:73]
	v_mul_f32_e32 v179, v82, v163
	v_cvt_pk_bf16_f32 v179, v179, v179
	global_store_short v3, v179, s[72:73] offset:64
	v_mul_f32_e32 v180, v50, v164
	v_cvt_pk_bf16_f32 v180, v180, v180
	global_store_short v3, v180, s[72:73] offset:128
	v_mul_f32_e32 v181, v18, v165
	v_cvt_pk_bf16_f32 v181, v181, v181
	global_store_short v3, v181, s[72:73] offset:192
	s_add_u32 s72, s72, 0x20000
	s_addc_u32 s73, s73, 0
	v_mul_f32_e32 v178, v115, v166
	v_cvt_pk_bf16_f32 v178, v178, v178
	global_store_short v3, v178, s[72:73]
	v_mul_f32_e32 v179, v83, v167
	v_cvt_pk_bf16_f32 v179, v179, v179
	global_store_short v3, v179, s[72:73] offset:64
	v_mul_f32_e32 v180, v51, v168
	v_cvt_pk_bf16_f32 v180, v180, v180
	global_store_short v3, v180, s[72:73] offset:128
	v_mul_f32_e32 v181, v19, v169
	v_cvt_pk_bf16_f32 v181, v181, v181
	global_store_short v3, v181, s[72:73] offset:192
	s_add_u32 s72, s72, 0x20000
	s_addc_u32 s73, s73, 0
	v_mul_f32_e32 v178, v116, v170
	v_cvt_pk_bf16_f32 v178, v178, v178
	global_store_short v3, v178, s[72:73]
	v_mul_f32_e32 v179, v84, v171
	v_cvt_pk_bf16_f32 v179, v179, v179
	global_store_short v3, v179, s[72:73] offset:64
	v_mul_f32_e32 v180, v52, v172
	v_cvt_pk_bf16_f32 v180, v180, v180
	global_store_short v3, v180, s[72:73] offset:128
	v_mul_f32_e32 v181, v20, v173
	v_cvt_pk_bf16_f32 v181, v181, v181
	global_store_short v3, v181, s[72:73] offset:192
	s_add_u32 s72, s72, 0x20000
	s_addc_u32 s73, s73, 0
	v_mul_f32_e32 v178, v117, v174
	v_cvt_pk_bf16_f32 v178, v178, v178
	global_store_short v3, v178, s[72:73]
	v_mul_f32_e32 v179, v85, v175
	v_cvt_pk_bf16_f32 v179, v179, v179
	global_store_short v3, v179, s[72:73] offset:64
	v_mul_f32_e32 v180, v53, v176
	v_cvt_pk_bf16_f32 v180, v180, v180
	global_store_short v3, v180, s[72:73] offset:128
	v_mul_f32_e32 v181, v21, v177
	v_cvt_pk_bf16_f32 v181, v181, v181
	global_store_short v3, v181, s[72:73] offset:192
